# GEMM-phase start stagger in four steps (bits 3 and 4 of the workgroup id) for the workgroups with a round of slack
# baseline (speedup 1.0000x reference)
; __global__ void __launch_bounds__(NWAVES * 64, 2) hymba_fwd(Args A) {
;     ...
;     XcdBarrier bar = xcd_barrier_post((unsigned*)ws, bst);
;     {
;         pg8::Gemm g{(const pg8::bf16_t*)(ws + WS_XA), (const pg8::bf16_t*)(ws + WS_W1), M1, DIN, DM, DM};
;         pg8::StaticOrder S; S.init(M1, DIN, G, bx);
;         pg8::Epi1 E{(const float*)(ws + WS_RS1), (const float*)(ws + WS_ROPE), A.out, (pg8::bf16_t*)(ws + WS_QD), (pg8::bf16_t*)(ws + WS_QS), (pg8::bf16_t*)(ws + WS_KD), (pg8::bf16_t*)(ws + WS_KS),
;                     (pg8::bf16_t*)(ws + WS_VDT), (pg8::bf16_t*)(ws + WS_VST)};
;         pg8::gemm_phase<pg8::Epi1, pg8::StaticOrder, true, true>(lds, g, S, E);
.Lstag_p1_b:
	s_bitcmp1_b32 s22, 4
	s_cbranch_scc0 .Lstag_p1
	s_sleep 127
	s_sleep 127
	s_sleep 127
	s_sleep 127
